# out-proj second round as half tiles too; FFN weight conversion part 0 moved from after the out-proj GEMM to the start of the norm-2 phase on all workgroups
# speedup vs baseline: 1.0020x; 1.0020x over previous
_Z14fwd_megakernel6Params:
	v_and_b32_e32 v163, 0x3ff, v0
	v_writelane_b32 v254, s2, 0
	s_add_u32 s2, s0, 0x120
	s_addc_u32 s3, s1, 0
	v_writelane_b32 v254, s2, 1
	v_and_b32_e32 v0, 0x3fffffff, v0
	v_mbcnt_lo_u32_b32 v203, -1, 0
	v_writelane_b32 v254, s3, 2
	v_writelane_b32 v254, s0, 3
	v_mbcnt_hi_u32_b32 v204, -1, v203
	v_and_b32_e32 v205, 64, v204
	v_writelane_b32 v254, s1, 4
	s_load_dword s0, s[0:1], 0x120
	s_mov_b32 s1, 0
	s_movk_i32 s33, 0x6000
	v_mov_b32_e32 v1, 0
	v_mov_b32_e32 v162, 0x358637bd
	s_waitcnt lgkmcnt(0)
	v_writelane_b32 v254, s0, 5
	s_cmp_eq_u32 s0, 0x100
	s_cselect_b32 s2, 1, 0
	v_writelane_b32 v255, s2, 41
	s_mov_b32 s2, 0
	v_writelane_b32 v255, s2, 42
	s_add_i32 s0, 0, 0x23fc0
	v_writelane_b32 v254, s0, 6
	s_add_i32 s0, 0, 0x19800
	v_writelane_b32 v254, s0, 7
	s_add_i32 s0, 0, 0x22400
	v_writelane_b32 v254, s0, 8
	s_add_i32 s0, 0, 0x22200
	v_writelane_b32 v254, s0, 9
	s_add_i32 s0, 0, 0x22000
	v_writelane_b32 v254, s0, 10
	s_add_i32 s0, 0, 0x11000
	v_writelane_b32 v254, s0, 11
	s_add_i32 s0, 0, 0x8800
	v_writelane_b32 v254, s0, 12
	s_add_i32 s0, 0, 0x225fc
	v_writelane_b32 v254, s0, 13
	s_add_i32 s0, 0, 0x221fc
	v_writelane_b32 v254, s0, 14
	s_add_i32 s0, 0, 0x23fe0
	v_writelane_b32 v254, s0, 15
	s_add_i32 s0, 0, 0x23fe4
	v_writelane_b32 v254, s0, 16
	s_mov_b32 s0, 0
	v_writelane_b32 v254, s0, 17
	v_writelane_b32 v254, s0, 18
	v_writelane_b32 v254, s0, 19
	s_mov_b32 s94, 0x30000
	v_mov_b32_e32 v171, 1
	v_writelane_b32 v254, s1, 20
	v_cmp_eq_u32_e64 s[0:1], 0, v0
	v_mov_b32_e32 v202, 0x2000
	v_add_u32_e32 v206, 64, v205
	v_writelane_b32 v254, s0, 21
	v_xor_b32_e32 v207, 32, v204
	v_xor_b32_e32 v208, 16, v204
	v_writelane_b32 v254, s1, 22
	s_mov_b64 s[0:1], 0
	v_writelane_b32 v254, s0, 23
	v_xor_b32_e32 v209, 8, v204
	v_xor_b32_e32 v220, 4, v204
	v_xor_b32_e32 v217, 2, v204
	v_xor_b32_e32 v212, 1, v204
	v_mov_b32_e32 v213, 0x7ff
	v_mov_b32_e32 v214, 0xff
	v_mov_b32_e32 v215, 0xffffff03
	v_mov_b64_e32 v[164:165], 0x17f
	v_mov_b64_e32 v[166:167], 0x180
	v_mov_b32_e32 v168, 0xff800000
	v_mov_b32_e32 v216, 0x800
	v_mov_b32_e32 v170, 0x3ecc95a3
	v_mov_b32_e32 v218, 0x7f800000
	v_mov_b32_e32 v219, 0x7fc00000
	v_mov_b32_e32 v221, 0x100
	v_mov_b32_e32 v222, 0x3f549a78
	v_mov_b32_e32 v223, 0x3fd49a78
	v_mov_b32_e32 v224, 0x42800000
	v_not_b32_e32 v225, 63
	v_not_b32_e32 v226, 31
	v_mov_b32_e32 v227, 0x6000
	v_mov_b32_e32 v228, 0x5000
	s_mov_b32 s95, 0x48000
	v_writelane_b32 v254, s1, 24
	s_mov_b64 s[92:93], 0x80
	s_branch .LBB0_3

.LBB0_282:
	v_readlane_b32 s98, v255, 41
	s_cmp_lg_u32 s98, 0
	s_cbranch_scc0 .Lcv_q7_body
	s_mov_b32 s98, 1
	v_writelane_b32 v255, s98, 42
	s_mov_b32 s0, 0
	s_branch .LBB0_356

.LBB0_354:
	v_readlane_b32 s0, v254, 5
	s_waitcnt lgkmcnt(0)
	s_barrier
	v_readlane_b32 s98, v255, 41
	s_cmp_lg_u32 s98, 0
	s_cbranch_scc1 .LBB0_516
	s_abs_i32 s0, s0
	v_cvt_f32_u32_e32 v0, s0
	s_sub_i32 s1, 0, s0
	v_rcp_iflag_f32_e32 v0, v0
	s_nop 0
	v_mul_f32_e32 v0, 0x4f7ffffe, v0
	v_cvt_u32_f32_e32 v0, v0
	s_nop 0
	v_readfirstlane_b32 s2, v0
	s_mul_i32 s1, s1, s2
	s_mul_hi_u32 s1, s2, s1
	s_add_i32 s2, s2, s1
	s_mul_hi_u32 s1, s2, 0x180
	s_mul_i32 s1, s1, s0
	s_sub_i32 s1, 0x180, s1
	s_sub_i32 s2, s1, s0
	s_cmp_ge_u32 s1, s0
	s_cselect_b32 s1, s2, s1
	s_sub_i32 s2, s1, s0
	s_cmp_ge_u32 s1, s0
	s_cselect_b32 s0, s2, s1
	s_cmp_lg_u32 s0, 0
	s_cbranch_scc1 .LBB0_356
	v_readlane_b32 s0, v254, 5

.LBB0_516:
	v_readlane_b32 s98, v255, 42
	s_cmp_lg_u32 s98, 0
	s_cbranch_scc0 .Lcv_exit_norm
	s_mov_b32 s98, 0
	v_writelane_b32 v255, s98, 42
	s_branch .Lcv_q7_body
